# stack6: stack5 + layer-0 pre-norm row pass issues all 12 loads of a row together (counted vmcnt)
# speedup vs baseline: 1.0448x; 1.0105x over previous
; DI unsigned pk2(float a, float b) { f32x2 v = {a, b}; bf2_t r = __builtin_convertvector(v, bf2_t); return __builtin_bit_cast(unsigned, r); }
; DI void phase1(const Params& p) {
;     ...
;     for (int row = gw; row < NTOK; row += nw) {
;         const float* src = row < NLAT ? p.x + (size_t)row * DM : p.ctx + (size_t)(row - NLAT) * DM;
;         const int cond = row < NLAT ? (row >> 12) : 4;
;         const float* mp = p.mod + ((size_t)cond) * 6144;
;         f32x4 v[4];
;         float ss = 0.f;
; #pragma unroll
;         for (int i = 0; i < 4; ++i) { v[i] = *(const f32x4*)(src + i * 256 + lane * 4); ss += v[i][0] * v[i][0] + v[i][1] * v[i][1] + v[i][2] * v[i][2] + v[i][3] * v[i][3]; }
; #pragma unroll
;         for (int o = 1; o < 64; o <<= 1) ss += __shfl_xor(ss, o);
;         if (lane < 16) p.ss[(size_t)row * 16 + lane] = lane == 0 ? ss : 0.f;
;         bf16_t* hp = p.H + (size_t)row * DM;
; #pragma unroll
;         for (int i = 0; i < 4; ++i) {
;             const int idx = i * 256 + lane * 4;
;             const f32x4 gg = *(const f32x4*)(p.norm1_g + idx), sc = *(const f32x4*)(mp + DM + idx);
;             f32x4 y;
; #pragma unroll
;             for (int j = 0; j < 4; ++j) y[j] = v[i][j] * gg[j] * (1.f + sc[j]);
;             u32x2 w; w[0] = pk2(y[0], y[1]); w[1] = pk2(y[2], y[3]);
;             *(u32x2*)(hp + idx) = w;
;         }
;     }
.LBB0_13:
	s_or_b64 exec, exec, s[6:7]
	s_waitcnt vmcnt(0) lgkmcnt(0)
	v_lshl_add_u64 v[30:31], v[30:31], 0, s[36:37]
	s_movk_i32 s6, 0x43ff
	v_cmp_lt_i32_e64 s[6:7], s6, v30
	v_lshl_add_u64 v[20:21], v[20:21], 0, s[38:39]
	s_or_b64 s[42:43], s[6:7], s[42:43]
	v_pk_mul_f32 v[10:11], v[10:11], v[66:67]
	v_pk_mul_f32 v[8:9], v[8:9], v[64:65]
	v_pk_add_f32 v[40:41], v[80:81], 1.0 op_sel_hi:[1,0]
	v_pk_add_f32 v[42:43], v[82:83], 1.0 op_sel_hi:[1,0]
	v_pk_mul_f32 v[8:9], v[8:9], v[40:41]
	v_pk_mul_f32 v[10:11], v[10:11], v[42:43]
	v_cvt_pk_bf16_f32 v8, v8, v9
	v_cvt_pk_bf16_f32 v9, v10, v11
	global_store_dwordx2 v[22:23], v[8:9], off
	v_pk_mul_f32 v[6:7], v[6:7], v[70:71]
	v_pk_mul_f32 v[4:5], v[4:5], v[68:69]
	v_pk_add_f32 v[40:41], v[84:85], 1.0 op_sel_hi:[1,0]
	v_pk_add_f32 v[42:43], v[86:87], 1.0 op_sel_hi:[1,0]
	v_pk_mul_f32 v[4:5], v[4:5], v[40:41]
	v_pk_mul_f32 v[6:7], v[6:7], v[42:43]
	v_cvt_pk_bf16_f32 v4, v4, v5
	v_cvt_pk_bf16_f32 v5, v6, v7
	global_store_dwordx2 v[22:23], v[4:5], off offset:512
	v_pk_mul_f32 v[14:15], v[14:15], v[74:75]
	v_pk_mul_f32 v[12:13], v[12:13], v[72:73]
	v_pk_add_f32 v[40:41], v[88:89], 1.0 op_sel_hi:[1,0]
	v_pk_add_f32 v[42:43], v[90:91], 1.0 op_sel_hi:[1,0]
	v_pk_mul_f32 v[12:13], v[12:13], v[40:41]
	v_pk_mul_f32 v[14:15], v[14:15], v[42:43]
	v_cvt_pk_bf16_f32 v12, v12, v13
	v_cvt_pk_bf16_f32 v13, v14, v15
	global_store_dwordx2 v[22:23], v[12:13], off offset:1024
	v_pk_mul_f32 v[62:63], v[62:63], v[78:79]
	v_pk_mul_f32 v[60:61], v[60:61], v[76:77]
	v_pk_add_f32 v[40:41], v[92:93], 1.0 op_sel_hi:[1,0]
	v_pk_add_f32 v[42:43], v[94:95], 1.0 op_sel_hi:[1,0]
	v_pk_mul_f32 v[60:61], v[60:61], v[40:41]
	v_pk_mul_f32 v[62:63], v[62:63], v[42:43]
	v_cvt_pk_bf16_f32 v60, v60, v61
	v_cvt_pk_bf16_f32 v61, v62, v63
	global_store_dwordx2 v[22:23], v[60:61], off offset:1536
	v_lshl_add_u64 v[22:23], v[22:23], 0, s[40:41]
	s_andn2_b64 exec, exec, s[42:43]
	s_cbranch_execz .LBB0_16
.LBB0_14:
	v_cmp_gt_i32_e64 s[6:7], s33, v30
	v_add_u32_e32 v0, 0xffffc000, v30
	v_mov_b32_e32 v2, s17
	v_mov_b32_e32 v3, s13
	v_cndmask_b32_e64 v1, 0, v31, s[6:7]
	v_cndmask_b32_e64 v0, v0, v30, s[6:7]
	v_cndmask_b32_e64 v3, v2, v3, s[6:7]
	v_mov_b32_e32 v2, s16
	v_mov_b32_e32 v4, s12
	v_cndmask_b32_e64 v2, v2, v4, s[6:7]
	v_lshlrev_b64 v[0:1], 12, v[0:1]
	v_lshl_add_u64 v[0:1], v[2:3], 0, v[0:1]
	v_lshl_add_u64 v[0:1], v[0:1], 0, v[192:193]
	global_load_dwordx4 v[8:11], v[0:1], off
	global_load_dwordx4 v[4:7], v[0:1], off offset:1024
	global_load_dwordx4 v[12:15], v[0:1], off offset:2048
	global_load_dwordx4 v[60:63], v[0:1], off offset:3072
	global_load_dwordx4 v[64:67], v[16:17], off
	global_load_dwordx4 v[68:71], v[16:17], off offset:1024
	global_load_dwordx4 v[72:75], v[16:17], off offset:2048
	global_load_dwordx4 v[76:79], v[16:17], off offset:3072
	v_min_i32_e32 v96, 0x4000, v30
	v_ashrrev_i32_e32 v96, 12, v96
	v_mul_hi_i32_i24_e32 v99, 0x6000, v96
	v_mul_i32_i24_e32 v98, 0x6000, v96
	v_lshl_add_u64 v[98:99], s[66:67], 0, v[98:99]
	s_mov_b64 s[6:7], 0x1000
	v_lshl_add_u64 v[98:99], v[98:99], 0, s[6:7]
	v_lshl_add_u64 v[100:101], v[98:99], 0, v[192:193]
	global_load_dwordx4 v[80:83], v[100:101], off
	v_lshl_add_u64 v[100:101], v[98:99], 0, v[24:25]
	global_load_dwordx4 v[84:87], v[100:101], off
	v_lshl_add_u64 v[100:101], v[98:99], 0, v[26:27]
	global_load_dwordx4 v[88:91], v[100:101], off
	v_lshl_add_u64 v[100:101], v[98:99], 0, v[28:29]
	global_load_dwordx4 v[92:95], v[100:101], off
	s_waitcnt vmcnt(11)
	v_mul_f32_e32 v2, v9, v9
	s_waitcnt vmcnt(10)
	v_mul_f32_e32 v3, v5, v5
	v_fmac_f32_e32 v2, v8, v8
	v_fmac_f32_e32 v3, v4, v4
	v_fmac_f32_e32 v2, v10, v10
	v_fmac_f32_e32 v3, v6, v6
	v_fmac_f32_e32 v2, v11, v11
	v_fmac_f32_e32 v3, v7, v7
	v_add_f32_e32 v2, v2, v3
	s_waitcnt vmcnt(9)
	v_mul_f32_e32 v3, v13, v13
	v_fmac_f32_e32 v3, v12, v12
	v_fmac_f32_e32 v3, v14, v14
	v_fmac_f32_e32 v3, v15, v15
	v_add_f32_e32 v19, v2, v3
	s_waitcnt vmcnt(8)
	v_mul_f32_e32 v40, v61, v61
	v_fmac_f32_e32 v40, v60, v60
	v_fmac_f32_e32 v40, v62, v62
	v_fmac_f32_e32 v40, v63, v63
	v_add_f32_e32 v19, v19, v40
	ds_bpermute_b32 v40, v34, v19
	s_waitcnt lgkmcnt(0)
	v_add_f32_e32 v19, v19, v40
	ds_bpermute_b32 v40, v35, v19
	s_waitcnt lgkmcnt(0)
	v_add_f32_e32 v19, v19, v40
	ds_bpermute_b32 v40, v36, v19
	s_waitcnt lgkmcnt(0)
	v_add_f32_e32 v19, v19, v40
	ds_bpermute_b32 v40, v37, v19
	s_waitcnt lgkmcnt(0)
	v_add_f32_e32 v19, v19, v40
	ds_bpermute_b32 v40, v38, v19
	s_waitcnt lgkmcnt(0)
	v_add_f32_e32 v19, v19, v40
	ds_bpermute_b32 v40, v39, v19
	s_and_saveexec_b64 s[6:7], vcc
	s_cbranch_execz .LBB0_13
	s_waitcnt lgkmcnt(0)
	v_add_f32_e32 v19, v19, v40
	v_cndmask_b32_e64 v19, 0, v19, s[4:5]
	global_store_dword v[20:21], v19, off
	s_branch .LBB0_13
